# lnpass (phase 14) run by the 128 scan WGs inside phase 6 after a sub-barrier; phase 14 and its grid barrier removed
# speedup vs baseline: 1.0052x; 1.0052x over previous
; #define LAS __attribute__((address_space(3)))
;     __device__ __forceinline__ const float* in(int i) const { return (const float*)ptr(i); }
;     __device__ __forceinline__ float* out() const { return (float*)ptr(36); }
;     __device__ __forceinline__ unsigned char* ws() const { return (unsigned char*)ptr(37); }
; #define ws (p.ws())
; __device__ __forceinline__ void att_sample_unit(const Ctx& p, int bs, int h, LAS unsigned char* lds) {
;     const int tid = threadIdx.x, lane = tid & 63, wave = __builtin_amdgcn_readfirstlane(tid >> 6), q = lane & 15, g = lane >> 4;
;     bf16_t* QB = (bf16_t*)(p.ws() + WS_QB);
;     const int row = MPR + bs * 16 + q;
;     bf16_t* qrow = QB + (size_t)row * 512 + h * 128;
;     bf16x8 bq[2][2];
; #pragma unroll
;     for (int mm = 0; mm < 2; ++mm)
; #pragma unroll
;         for (int ks = 0; ks < 2; ++ks) bq[mm][ks] = *(const bf16x8*)(qrow + mm * 64 + ks * 32 + 8 * g);
;     AttAcc A; att_init(A);
;     for (int kt = wave; kt < 65; kt += 8) {
;         const bool isnew = kt == 64;
;         const float* kb = isnew ? p.out() + O_KS + (size_t)bs * 16 * 512 : p.in(2) + ((size_t)bs * PAST + kt * 64) * 512;
;         const float* vb = isnew ? p.out() + O_VS + (size_t)bs * 16 * 512 : p.in(3) + ((size_t)bs * PAST + kt * 64) * 512;
;         const int nvalid = isnew ? 16 : 64;
; __device__ __forceinline__ void phase_mixer(const Ctx& p, LAS unsigned char* lds) {
;     if (blockIdx.x < 128) scan_unit(p, blockIdx.x >> 2, blockIdx.x & 3, lds);
;     else { const int u0 = (blockIdx.x - 128) * 2; scan_unit(p, 32 + (u0 >> 2), u0 & 3, lds); scan_unit(p, 32 + ((u0 + 1) >> 2), (u0 + 1) & 3, lds); }
;     if (blockIdx.x < 128) return;
;     unsigned* ctr = (unsigned*)(p.ws() + WS_CTR);
;     LAS unsigned* su = (LAS unsigned*)(lds + 140 * 1024);
;     for (;;) {
;         __syncthreads();
;         if (threadIdx.x == 0) su[0] = atomicAdd(ctr, 1u);
;         __syncthreads();
;         const int u = __builtin_amdgcn_readfirstlane((int)su[0]);
;         if (u >= 32) break;
;         att_sample_unit(p, u >> 2, u & 3, lds);
.LBB0_1750:
	s_andn2_b64 vcc, exec, s[6:7]
	s_cbranch_vccnz .Lscan_ffn2w
	s_waitcnt vmcnt(0) lgkmcnt(0)
	s_barrier
	v_cmp_eq_u32_e32 vcc, 0, v180
	s_and_saveexec_b64 s[2:3], vcc
	s_cbranch_execz .Lln_sig_done
	v_mov_b32_e32 v0, 0x23528
	ds_read_b64 v[0:1], v0
	s_waitcnt lgkmcnt(0)
	v_readfirstlane_b32 s4, v0
	v_readfirstlane_b32 s5, v1
	s_nop 4
	s_add_u32 s4, s4, 0x3180320
	s_addc_u32 s5, s5, 0
	buffer_wbl2 sc1
	s_waitcnt vmcnt(0)
	v_mov_b32_e32 v0, 0
	v_mov_b32_e32 v1, 1
	global_atomic_add v0, v1, s[4:5]
.Lln_sig_done:
	s_or_b64 exec, exec, s[2:3]
	s_add_i32 s2, 0, 0x23528
	v_mov_b32_e32 v117, s2
	s_waitcnt vmcnt(0)
	ds_read_b64 v[0:1], v117
	v_and_b32_e32 v132, 63, v180
	v_and_b32_e32 v135, 15, v180
	s_mov_b32 s43, 0
	v_or_b32_e32 v133, 0x4000, v135
	s_waitcnt lgkmcnt(0)
	v_readfirstlane_b32 s33, v0
	v_readfirstlane_b32 s34, v1
	s_add_u32 s44, s33, 0x3180000
	v_bfe_u32 v0, v180, 4, 2
	s_addc_u32 s45, s34, 0
	v_lshlrev_b32_e32 v134, 2, v0
	v_lshlrev_b32_e32 v116, 3, v0
	v_lshlrev_b32_e32 v0, 2, v132
	s_add_i32 s2, 0, 0x20000
	v_add_u32_e32 v162, s2, v0
	s_add_i32 s2, 0, 0x22000
	v_add_u32_e32 v161, 0, v0
	v_add_u32_e32 v163, s2, v0
	s_add_i32 s35, 0, 0x23000
	v_mbcnt_lo_u32_b32 v0, -1, 0
	v_mov_b32_e32 v1, 0
	v_or_b32_e32 v142, 16, v135
	v_or_b32_e32 v144, 32, v135
	v_or_b32_e32 v145, 48, v135
	v_or_b32_e32 v146, 1, v134
	v_or_b32_e32 v147, 2, v134
	v_or_b32_e32 v148, 3, v134
	v_or_b32_e32 v149, 16, v134
	v_or_b32_e32 v150, 17, v134
	v_or_b32_e32 v151, 18, v134
	v_or_b32_e32 v152, 19, v134
	v_or_b32_e32 v153, 32, v134
	v_or_b32_e32 v154, 33, v134
	v_or_b32_e32 v155, 34, v134
	v_or_b32_e32 v156, 35, v134
	v_or_b32_e32 v157, 48, v134
	v_or_b32_e32 v158, 49, v134
	v_or_b32_e32 v159, 50, v134
	v_or_b32_e32 v160, 51, v134
	v_mov_b32_e32 v164, s35
	s_mov_b64 s[46:47], 0x5280000
	s_add_i32 s56, 0, 0x23410
	s_add_i32 s57, 0, 0x23520
	s_add_i32 s58, 0, 0x23418
	s_mov_b32 s59, 0xf149f2ca
	s_add_i32 s60, 0, 0x23460
	s_add_i32 s61, 0, 0x23470
	s_mov_b32 s62, 0x3fb8aa3b
	s_mov_b32 s63, 0xc2ce8ed0
	s_mov_b32 s64, 0x42b17218
	v_mov_b32_e32 v118, 0x3e4ccccd
	v_mov_b32_e32 v165, 0x358637bd
	s_mov_b32 s65, 0xf800000
	v_mov_b32_e32 v166, 0x260
	s_mov_b32 s66, 0x3f4ccccd
	s_add_i32 s67, 0, 0x23480
	v_lshlrev_b32_e32 v136, 1, v116
	v_mov_b32_e32 v167, 0xf149f2ca
	v_mbcnt_hi_u32_b32 v143, -1, v0
	v_mov_b32_e32 v168, 0x7f800000
	s_branch .LBB0_1755

;     __device__ __forceinline__ unsigned char* ws() const { return (unsigned char*)ptr(37); }
; #define ws (p.ws())
; __device__ __forceinline__ void sub_barrier(const Ctx& p, unsigned n) {
;     asm volatile("s_waitcnt vmcnt(0)" ::: "memory");
;     __syncthreads();
;     if (threadIdx.x == 0) {
;         unsigned* c = (unsigned*)(p.ws() + WS_CTR) + 128;
;         __builtin_amdgcn_fence(__ATOMIC_RELEASE, "agent");
;         asm volatile("s_waitcnt vmcnt(0)" ::: "memory");
;         __hip_atomic_fetch_add(c, 1u, __ATOMIC_RELAXED, __HIP_MEMORY_SCOPE_AGENT);
;         while (__hip_atomic_load(c, __ATOMIC_RELAXED, __HIP_MEMORY_SCOPE_AGENT) < n) __builtin_amdgcn_s_sleep(20);
;         __builtin_amdgcn_fence(__ATOMIC_ACQUIRE, "agent");
;         asm volatile("s_waitcnt vmcnt(0)" ::: "memory");
;     }
;     __syncthreads();
; }
.Lffn2w_done:
	s_waitcnt vmcnt(0) lgkmcnt(0)
	s_barrier
	v_cmp_eq_u32_e32 vcc, 0, v180
	s_and_saveexec_b64 s[2:3], vcc
	s_cbranch_execz .Lln_sync_done
	v_mov_b32_e32 v0, 0x23528
	ds_read_b64 v[0:1], v0
	s_waitcnt lgkmcnt(0)
	v_readfirstlane_b32 s4, v0
	v_readfirstlane_b32 s5, v1
	s_nop 4
	s_add_u32 s4, s4, 0x3180300
	s_addc_u32 s5, s5, 0
	buffer_wbl2 sc1
	s_waitcnt vmcnt(0)
	v_mov_b32_e32 v0, 0
	v_mov_b32_e32 v1, 1
	global_atomic_add v0, v1, s[4:5]
.Lln_spin_a:
	global_load_dword v1, v0, s[4:5] sc1
	s_waitcnt vmcnt(0)
	v_cmp_gt_u32_e32 vcc, 0x80, v1
	s_cbranch_vccz .Lln_spin_b
	s_sleep 8
	s_branch .Lln_spin_a
.Lln_spin_b:
	global_load_dword v1, v0, s[4:5] offset:32 sc1
	s_waitcnt vmcnt(0)
	v_cmp_gt_u32_e32 vcc, 0x80, v1
	s_cbranch_vccz .Lln_spin_done
	s_sleep 8
	s_branch .Lln_spin_b

;     __device__ __forceinline__ const float* in(int i) const { return (const float*)ptr(i); }
;     __device__ __forceinline__ unsigned char* ws() const { return (unsigned char*)ptr(37); }
; #define ws (p.ws())
; __device__ __forceinline__ void phase_lnpass(const Ctx& p) {
;     const int tid = threadIdx.x, c8 = tid & 7, h = (tid >> 3) & 7, rr = tid >> 6, c = h * 64 + 8 * c8;
;     const bf16_t* ZRW = (const bf16_t*)(p.ws() + WS_ZRW); const bf16_t* AB = (const bf16_t*)(p.ws() + WS_ABUF); const bf16_t* GG = (const bf16_t*)(p.ws() + WS_GG);
;     bf16_t* ORW = (bf16_t*)(p.ws() + WS_ORW);
;     float mur[8], muk[8], muv[8], kac[8], rkc[8], lg[8], lb[8];
; #pragma unroll
;     for (int e = 0; e < 8; ++e) { mur[e] = p.in(17)[c + e]; muk[e] = p.in(17)[512 + c + e]; muv[e] = p.in(17)[1024 + c + e]; kac[e] = p.in(24)[c + e]; rkc[e] = p.in(25)[c + e]; lg[e] = p.in(26)[c + e]; lb[e] = p.in(27)[c + e]; }
;     struct LR { u32x4 zr, zrp, zk, zkp, zv, zvp, ab, gg, yy; };
;     auto ldrow = [&](LR& L, int row) {
;         const int rp = row > 0 ? row - 1 : 0;
;         L.zr = *(const u32x4*)(ZRW + (size_t)row * SHW + c); L.zrp = *(const u32x4*)(ZRW + (size_t)rp * SHW + c);
;         L.zk = *(const u32x4*)(ZRW + (size_t)row * SHW + 512 + c); L.zkp = *(const u32x4*)(ZRW + (size_t)rp * SHW + 512 + c);
;         L.zv = *(const u32x4*)(ZRW + (size_t)row * SHW + 1024 + c); L.zvp = *(const u32x4*)(ZRW + (size_t)rp * SHW + 1024 + c);
;         L.ab = *(const u32x4*)(AB + (size_t)row * 512 + c); L.gg = *(const u32x4*)(GG + (size_t)row * 512 + c); L.yy = *(const u32x4*)(ORW + (size_t)row * 512 + c);
;     };
;     LR La, Lb;
;     if ((int)blockIdx.x < MR / 8) ldrow(La, blockIdx.x * 8 + rr);
;     for (int it = blockIdx.x; it < MR / 8; it += gridDim.x) {
;         const int row = it * 8 + rr;
;         const bool more = it + (int)gridDim.x < MR / 8;
;         if (more) ldrow(Lb, (it + gridDim.x) * 8 + rr);
.Lln_sync_done:
	s_or_b64 exec, exec, s[2:3]
	s_waitcnt lgkmcnt(0)
	s_barrier
	s_movk_i32 s72, 0x80
	s_add_i32 s2, 0, 0x23528
	s_waitcnt vmcnt(0)
	v_mov_b32_e32 v0, s2
	ds_read_b64 v[0:1], v0
	s_add_i32 s2, 0, 0x23488
	v_mov_b32_e32 v2, s2
	s_add_i32 s6, 0, 0x234c0
	ds_read_b64 v[8:9], v2
	s_waitcnt lgkmcnt(0)
	v_readfirstlane_b32 s2, v0
	v_mov_b32_e32 v0, s6
	s_add_i32 s6, 0, 0x234d0
	v_mov_b32_e32 v4, s6
	v_readfirstlane_b32 s3, v1
	ds_read_b128 v[0:3], v0
	ds_read_b128 v[4:7], v4
	v_readfirstlane_b32 s12, v8
	v_readfirstlane_b32 s13, v9
	s_cmpk_gt_i32 s28, 0x80f
	s_waitcnt lgkmcnt(1)
	v_readfirstlane_b32 s14, v0
	v_readfirstlane_b32 s15, v1
	v_readfirstlane_b32 s16, v2
	v_readfirstlane_b32 s17, v3
	s_waitcnt lgkmcnt(0)
	v_readfirstlane_b32 s10, v4
	v_readfirstlane_b32 s11, v5
	v_readfirstlane_b32 s8, v6
	v_readfirstlane_b32 s9, v7
	s_cbranch_scc1 .Lln_done
	v_lshlrev_b32_e32 v0, 3, v180
	v_and_b32_e32 v56, 0x1f8, v0
	v_mov_b32_e32 v141, 0
	v_lshlrev_b32_e32 v140, 2, v56
	v_lshl_add_u64 v[32:33], s[12:13], 0, v[140:141]
	global_load_dwordx4 v[0:3], v140, s[12:13] offset:16
	global_load_dwordx4 v[4:7], v140, s[12:13]
	global_load_dwordx4 v[8:11], v140, s[12:13] offset:2064
	global_load_dwordx4 v[12:15], v140, s[12:13] offset:2048
	global_load_dwordx4 v[16:19], v140, s[14:15] offset:16
	global_load_dwordx4 v[20:23], v140, s[14:15]
	global_load_dwordx4 v[24:27], v140, s[16:17] offset:16
	global_load_dwordx4 v[28:31], v140, s[16:17]
	s_movk_i32 s12, 0x1000
	v_add_co_u32_e32 v60, vcc, s12, v32
	s_mov_b64 s[6:7], 0x1000
	s_nop 0
	v_addc_co_u32_e32 v61, vcc, 0, v33, vcc
	v_lshl_add_u64 v[58:59], v[32:33], 0, s[6:7]
	global_load_dwordx4 v[32:35], v[60:61], off
	global_load_dwordx4 v[36:39], v[58:59], off offset:16
	global_load_dwordx4 v[40:43], v140, s[10:11] offset:16
	global_load_dwordx4 v[44:47], v140, s[10:11]
	global_load_dwordx4 v[48:51], v140, s[8:9] offset:16
	global_load_dwordx4 v[52:55], v140, s[8:9]
	s_add_u32 s8, s2, 0x8340000
	s_addc_u32 s9, s3, 0
	s_add_u32 s10, s2, 0x4240000
	s_addc_u32 s11, s3, 0
	s_add_u32 s14, s2, 0x3200000
	v_lshrrev_b32_e32 v152, 6, v180
	s_addc_u32 s15, s3, 0
	s_lshl_b32 s12, s28, 3
	v_add_u32_e32 v58, s12, v152
	v_max_i32_e32 v57, 1, v58
	s_movk_i32 s13, 0xe00
	v_mov_b64_e32 v[60:61], s[8:9]
	v_add_u32_e32 v57, -1, v57
	v_mad_i64_i32 v[62:63], s[16:17], v58, s13, v[60:61]
	v_lshlrev_b32_e32 v140, 1, v56
	v_lshl_add_u64 v[62:63], v[62:63], 0, v[140:141]
	v_mad_u64_u32 v[60:61], s[16:17], v57, s13, v[60:61]
	v_ashrrev_i32_e32 v59, 31, v58
	v_lshl_add_u64 v[60:61], v[60:61], 0, v[140:141]
	global_load_dwordx4 v[104:107], v[62:63], off
	global_load_dwordx4 v[108:111], v[62:63], off offset:1024
	global_load_dwordx4 v[124:127], v[60:61], off
	global_load_dwordx4 v[92:95], v[62:63], off offset:2048
	global_load_dwordx4 v[116:119], v[60:61], off offset:1024
	global_load_dwordx4 v[120:123], v[60:61], off offset:2048
	v_lshlrev_b64 v[58:59], 10, v[58:59]
	v_lshl_add_u64 v[60:61], s[14:15], 0, v[58:59]
	v_lshl_add_u64 v[62:63], s[10:11], 0, v[58:59]
	v_lshl_add_u64 v[58:59], s[2:3], 0, v[58:59]
	v_lshl_add_u64 v[60:61], v[60:61], 0, v[140:141]
	v_lshl_add_u64 v[58:59], v[58:59], 0, v[140:141]
	v_lshl_add_u64 v[62:63], v[62:63], 0, v[140:141]
	global_load_dwordx4 v[112:115], v[60:61], off
	global_load_dwordx4 v[100:103], v[62:63], off
	global_load_dwordx4 v[96:99], v[58:59], off
	v_lshl_add_u64 v[146:147], s[2:3], 0, v[140:141]
	s_add_i32 s2, s28, s72
	v_lshl_add_u64 v[142:143], s[14:15], 0, v[140:141]
	v_lshl_add_u64 v[144:145], s[10:11], 0, v[140:141]
	v_lshl_add_u64 v[148:149], s[8:9], 0, v[140:141]
	s_lshl_b32 s14, s2, 3
	s_lshl_b32 s15, s72, 3
	s_movk_i32 s16, 0x4000
	s_movk_i32 s17, 0x3fff
	s_add_i32 s18, 0, 0x23428
	s_movk_i32 s19, 0x1c00
	v_lshlrev_b32_e32 v140, 2, v56
	v_mov_b32_e32 v153, 0x3a27c5ac
	s_mov_b32 s20, 0xf800000
	v_mov_b32_e32 v154, 0x260
	v_mov_b32_e32 v155, 0xfff
	s_mov_b32 s21, s28
	s_branch .Lln_c

;     __device__ __forceinline__ const float* in(int i) const { return (const float*)ptr(i); }
; __device__ __forceinline__ void unpack8(const u32x4 w, float (&f)[8]) { f[0] = bflo(w.x); f[1] = bfhi(w.x); f[2] = bflo(w.y); f[3] = bfhi(w.y); f[4] = bflo(w.z); f[5] = bfhi(w.z); f[6] = bflo(w.w); f[7] = bfhi(w.w); }
; __device__ __forceinline__ void phase_lnpass(const Ctx& p) {
;     ...
;     auto ldrow = [&](LR& L, int row) {
;         const int rp = row > 0 ? row - 1 : 0;
;         L.zr = *(const u32x4*)(ZRW + (size_t)row * SHW + c); L.zrp = *(const u32x4*)(ZRW + (size_t)rp * SHW + c);
;         L.zk = *(const u32x4*)(ZRW + (size_t)row * SHW + 512 + c); L.zkp = *(const u32x4*)(ZRW + (size_t)rp * SHW + 512 + c);
;         L.zv = *(const u32x4*)(ZRW + (size_t)row * SHW + 1024 + c); L.zvp = *(const u32x4*)(ZRW + (size_t)rp * SHW + 1024 + c);
;         L.ab = *(const u32x4*)(AB + (size_t)row * 512 + c); L.gg = *(const u32x4*)(GG + (size_t)row * 512 + c); L.yy = *(const u32x4*)(ORW + (size_t)row * 512 + c);
;     };
;     ...
;     for (int it = blockIdx.x; it < MR / 8; it += gridDim.x) {
;         const int row = it * 8 + rr;
;         const bool more = it + (int)gridDim.x < MR / 8;
;         if (more) ldrow(Lb, (it + gridDim.x) * 8 + rr);
;         float zr[8], pr[8], zk[8], pk[8], zv[8], pv[8], a[8], g[8], y[8];
;         unpack8(La.zr, zr); unpack8(La.zrp, pr); unpack8(La.zk, zk); unpack8(La.zkp, pk); unpack8(La.zv, zv); unpack8(La.zvp, pv); unpack8(La.ab, a); unpack8(La.gg, g); unpack8(La.yy, y);
;         const bool first = row < MPR ? (row & (TP - 1)) == 0 : ((row - MPR) & 15) == 0;
;         if (first) {
; #pragma unroll
;             for (int e = 0; e < 8; ++e) { pr[e] = 0.f; pk[e] = 0.f; pv[e] = 0.f; }
;             if (row >= MPR) { const float* s0 = p.in(5) + (size_t)((row - MPR) >> 4) * SHW;
; #pragma unroll
;                 for (int e = 0; e < 8; ++e) { pr[e] = s0[c + e]; pk[e] = s0[512 + c + e]; pv[e] = s0[1024 + c + e]; } }
;         }
.Lln_c:
	s_add_i32 s21, s21, s72
	s_cmpk_gt_i32 s21, 0x80f
	s_cselect_b64 s[8:9], -1, 0
	s_and_b64 vcc, exec, s[8:9]
	s_cbranch_vccnz .Lln_d
	v_add_u32_e32 v80, s14, v152
	v_max_i32_e32 v56, 1, v80
	v_add_u32_e32 v56, -1, v56
	v_mad_i64_i32 v[68:69], s[2:3], v80, s13, v[148:149]
	v_mad_u64_u32 v[76:77], s[2:3], v56, s13, v[148:149]
	global_load_dwordx4 v[56:59], v[68:69], off
	global_load_dwordx4 v[64:67], v[68:69], off offset:1024
	global_load_dwordx4 v[60:63], v[76:77], off
	global_load_dwordx4 v[72:75], v[68:69], off offset:2048
	s_nop 0
	global_load_dwordx4 v[68:71], v[76:77], off offset:1024
	s_nop 0
	global_load_dwordx4 v[76:79], v[76:77], off offset:2048
	v_ashrrev_i32_e32 v81, 31, v80
	v_lshlrev_b64 v[88:89], 10, v[80:81]
	v_lshl_add_u64 v[80:81], v[142:143], 0, v[88:89]
	v_lshl_add_u64 v[84:85], v[144:145], 0, v[88:89]
	v_lshl_add_u64 v[88:89], v[146:147], 0, v[88:89]
	global_load_dwordx4 v[80:83], v[80:81], off
	s_nop 0
	global_load_dwordx4 v[84:87], v[84:85], off
	s_nop 0
	global_load_dwordx4 v[88:91], v[88:89], off
.Lln_d:
	v_add_u32_e32 v150, s12, v152
	v_cmp_gt_i32_e32 vcc, s16, v150
	s_waitcnt vmcnt(6)
	v_lshlrev_b32_e32 v132, 16, v124
	v_and_b32_e32 v133, 0xffff0000, v124
	v_cndmask_b32_e32 v151, 15, v155, vcc
	v_and_b32_e32 v151, v151, v150
	v_lshlrev_b32_e32 v134, 16, v125
	v_and_b32_e32 v135, 0xffff0000, v125
	v_lshlrev_b32_e32 v124, 16, v126
	v_and_b32_e32 v125, 0xffff0000, v126
	v_lshlrev_b32_e32 v126, 16, v127
	v_and_b32_e32 v127, 0xffff0000, v127
	s_waitcnt vmcnt(4)
	v_lshlrev_b32_e32 v136, 16, v116
	v_and_b32_e32 v137, 0xffff0000, v116
	v_lshlrev_b32_e32 v138, 16, v117
	v_and_b32_e32 v139, 0xffff0000, v117
	v_lshlrev_b32_e32 v128, 16, v118
	v_and_b32_e32 v129, 0xffff0000, v118
	v_lshlrev_b32_e32 v130, 16, v119
	v_and_b32_e32 v131, 0xffff0000, v119
	s_waitcnt vmcnt(3)
	v_lshlrev_b32_e32 v116, 16, v120
	v_and_b32_e32 v117, 0xffff0000, v120
	v_lshlrev_b32_e32 v118, 16, v121
	v_and_b32_e32 v119, 0xffff0000, v121
	v_lshlrev_b32_e32 v120, 16, v122
	v_and_b32_e32 v121, 0xffff0000, v122
	v_lshlrev_b32_e32 v122, 16, v123
	v_and_b32_e32 v123, 0xffff0000, v123
	v_cmp_eq_u32_e32 vcc, 0, v151
	s_and_saveexec_b64 s[2:3], vcc
	s_cbranch_execz .Lln_b
	v_cmp_lt_i32_e32 vcc, s17, v150
	v_mov_b32_e32 v127, 0
	v_mov_b32_e32 v126, 0
	v_mov_b32_e32 v125, 0
	v_mov_b32_e32 v124, 0
	v_mov_b32_e32 v135, 0
	v_mov_b32_e32 v134, 0
	v_mov_b32_e32 v133, 0
	v_mov_b32_e32 v132, 0
	v_mov_b32_e32 v131, 0
	v_mov_b32_e32 v130, 0
	v_mov_b32_e32 v129, 0
	v_mov_b32_e32 v128, 0
	v_mov_b32_e32 v139, 0
	v_mov_b32_e32 v138, 0
	v_mov_b32_e32 v137, 0
	v_mov_b32_e32 v136, 0
	v_mov_b32_e32 v123, 0
	v_mov_b32_e32 v122, 0
	v_mov_b32_e32 v121, 0
	v_mov_b32_e32 v120, 0
	v_mov_b32_e32 v119, 0
	v_mov_b32_e32 v118, 0
	v_mov_b32_e32 v117, 0
	v_mov_b32_e32 v116, 0
	s_and_saveexec_b64 s[10:11], vcc
	s_cbranch_execz .Lln_a
	v_mov_b32_e32 v116, s18
	ds_read_b64 v[116:117], v116
	v_add_u32_e32 v118, 0xffffc000, v150
	v_lshrrev_b32_e32 v118, 4, v118
	s_waitcnt lgkmcnt(0)
	v_readfirstlane_b32 s22, v116
	v_readfirstlane_b32 s23, v117
	s_nop 0
	v_mov_b32_e32 v116, s22
	v_mov_b32_e32 v117, s23
	v_mad_u64_u32 v[116:117], s[22:23], v118, s19, v[116:117]
	v_lshl_add_u64 v[116:117], v[116:117], 0, v[140:141]
	v_lshl_add_u64 v[120:121], v[116:117], 0, s[6:7]
	global_load_dwordx4 v[132:135], v[116:117], off
	global_load_dwordx4 v[124:127], v[116:117], off offset:16
	global_load_dwordx4 v[136:139], v[116:117], off offset:2048
	global_load_dwordx4 v[128:131], v[116:117], off offset:2064
	v_add_co_u32_e32 v116, vcc, 0x1000, v116
	s_nop 1
	v_addc_co_u32_e32 v117, vcc, 0, v117, vcc
	global_load_dwordx4 v[116:119], v[116:117], off
	s_nop 0
	global_load_dwordx4 v[120:123], v[120:121], off offset:16
	s_branch .Lln_a
.Lln_done:
.LBB0_1819:
	s_cmpk_lt_u32 s28, 0x80
	s_cbranch_scc1 .LBB0_1869
	s_waitcnt vmcnt(0)
	v_readlane_b32 s0, v238, 0
	v_readlane_b32 s1, v238, 1
	s_waitcnt vmcnt(0) lgkmcnt(0)
	s_barrier
	s_and_saveexec_b64 s[2:3], s[0:1]
	s_cbranch_execz .LBB0_1827
	s_add_i32 s4, 0, 0x23528
	v_mov_b32_e32 v0, s4
	ds_read_b64 v[0:1], v0
	s_mov_b64 s[6:7], exec
	buffer_wbl2 sc1
	s_waitcnt lgkmcnt(0)
	s_waitcnt vmcnt(0)
	v_readfirstlane_b32 s4, v0
	v_mbcnt_lo_u32_b32 v0, s6, 0
	v_readfirstlane_b32 s5, v1
	s_add_u32 s4, s4, 0x3180200
	v_mbcnt_hi_u32_b32 v0, s7, v0
	s_addc_u32 s5, s5, 0
	v_cmp_eq_u32_e32 vcc, 0, v0
	s_and_saveexec_b64 s[8:9], vcc
	s_cbranch_execz .LBB0_1823
	s_bcnt1_i32_b64 s6, s[6:7]
	v_mov_b32_e32 v0, 0
	v_mov_b32_e32 v1, s6
	global_atomic_add v0, v1, s[4:5]

;     __device__ __forceinline__ unsigned char* ws() const { return (unsigned char*)ptr(37); }
; #define ws (p.ws())
; #define SEAM(k) do { if (IN(k) && IN((k) + 1)) xcd_barrier(bar); } while (0)
; __global__ void __launch_bounds__(512) fwd_kernel(Params prm) {
;     ...
;     if (IN(14)) { phase_lnpass(p); } if (IN(14) && IN(7)) xcd_barrier(bar);
;     if (IN(8)) { EpiGate2 E{(const bf16_t*)(ws + WS_KB), (const bf16_t*)(ws + WS_GATE), (bf16_t*)(ws + WS_MG)}; run_gemm(lds, (const bf16_t*)(ws + WS_ORW), (const bf16_t*)(ws + WS_WRT), DM, 512, E); } SEAM(8);
.LBB0_1940:
	s_or_b64 exec, exec, s[2:3]
	s_waitcnt lgkmcnt(0)
	s_barrier
.LBB0_1941:
	s_branch .LBB0_2005
.LBB0_2005:
	s_cmp_lt_i32 s36, 9
	s_cselect_b64 s[2:3], -1, 0
	s_cmp_gt_i32 s37, 8
	s_cselect_b64 s[4:5], -1, 0
	s_and_b64 s[4:5], s[2:3], s[4:5]
	s_andn2_b64 vcc, exec, s[4:5]
	s_cbranch_vccnz .LBB0_2048
	s_add_i32 s2, 0, 0x23528
	s_waitcnt vmcnt(0)
	v_mov_b32_e32 v0, s2
	ds_read_b64 v[0:1], v0
	s_cmpk_lt_i32 s28, 0x104
	s_cselect_b64 s[2:3], -1, 0
	s_cmpk_gt_i32 s28, 0x103
	v_readfirstlane_b32 s16, v180
	s_waitcnt lgkmcnt(0)
	v_readfirstlane_b32 s33, v0
	v_readfirstlane_b32 s34, v1
	s_cbranch_scc1 .LBB0_2012
	s_ashr_i32 s6, s28, 31
	s_lshr_b32 s6, s6, 29
	s_add_i32 s8, s28, s6
	s_and_b32 s6, s8, -8
	s_sub_i32 s9, s28, s6
	s_cmp_gt_i32 s9, 3
	s_cbranch_scc0 .LBB0_2009
	s_lshl_b32 s6, s9, 5
	s_or_b32 s10, s6, 4
	s_cbranch_execz .LBB0_2010
	s_branch .LBB0_2011
